# A/B: remaining per-phase s_setprio 1/0 flips removed from the three GEMM K-loops (on top of v76)
# speedup vs baseline: 1.0033x; 1.0009x over previous
; #define PG8_STAGE(bufoff, gbase, voff) do { _Pragma("unroll") for (int _i = 0; _i < 2; ++_i) \
;         __builtin_amdgcn_global_load_lds((const unsigned*)((const char*)(gbase) + (voff)[_i]), (PG8_LAS unsigned*)(lds + (bufoff) + ldsw + _i * 8192), 16, 0, 0); } while (0)
; #define PG8_LDA(dst, b, h) do { _Pragma("unroll") for (int m = 0; m < 4; ++m) _Pragma("unroll") for (int k = 0; k < 2; ++k) dst[m][k] = *(const PG8_LAS bf16x8*)(lds + PG8_SA(b, h) + aoff + m * 2048 + k * 1024); } while (0)
; #define PG8_LDB(dst, b, h) do { _Pragma("unroll") for (int n = 0; n < 2; ++n) _Pragma("unroll") for (int k = 0; k < 2; ++k) dst[n][k] = *(const PG8_LAS bf16x8*)(lds + PG8_SB(b, h) + boff + n * 2048 + k * 1024); } while (0)
; #define PG8_MMA(ai, bj, At, Bt) do { __builtin_amdgcn_s_setprio(1); _Pragma("unroll") for (int m = 0; m < 4; ++m) _Pragma("unroll") for (int n = 0; n < 2; ++n) _Pragma("unroll") for (int k = 0; k < 2; ++k) \
;         acc[ai][bj][m][n] = __builtin_amdgcn_mfma_f32_16x16x32_bf16(Bt[n][k], At[m][k], acc[ai][bj][m][n], 0, 0, 0); __builtin_amdgcn_s_setprio(0); } while (0)
; #define PG8_WAIT_V(n) asm volatile("s_waitcnt vmcnt(" #n ")" ::: "memory")
; #define PG8_WAIT_L(n) asm volatile("s_waitcnt lgkmcnt(" #n ")" ::: "memory")
; #define PG8_BAR __builtin_amdgcn_s_barrier()
; #define PG8_SCHED __builtin_amdgcn_sched_barrier(0)
; template <class Epi, class Sched, bool ALIGN_EPI = false, bool SP2 = false>
; __device__ __forceinline__ void gemm_phase(PG8_LAS unsigned char* lds, const Gemm g, const Sched& S, const Epi& E) {
;     ...
;             PG8_LDB(B0, 0, 0); PG8_LDB(B1, 0, 1); PG8_SCHED; PG8_LDA(At, 0, 0); PG8_STAGE(PG8_SA(1, 1), a1 + hstep, voffA);
;             PG8_WAIT_V(8); PG8_WAIT_L(0); PG8_BAR; PG8_MMA(0, 0, At, B0); PG8_MMA(0, 1, At, B1); PG8_BAR; PG8_SCHED;
;             PG8_LDA(At, 0, 1); PG8_STAGE(PG8_SB(0, 0), b2, voffB); PG8_STAGE(PG8_SB(0, 1), b2 + hstep, voffB); PG8_STAGE(PG8_SA(0, 0), a2, voffA);
;             PG8_WAIT_V(8); PG8_WAIT_L(0); PG8_BAR; PG8_MMA(1, 0, At, B0); PG8_MMA(1, 1, At, B1); PG8_BAR; PG8_SCHED;
.LBB0_143:
	ds_read_b128 v[130:133], v193
	ds_read_b128 v[134:137], v193 offset:1024
	ds_read_b128 v[138:141], v193 offset:2048
	ds_read_b128 v[142:145], v193 offset:3072
	ds_read_b128 v[166:169], v194
	ds_read_b128 v[170:173], v194 offset:1024
	ds_read_b128 v[174:177], v194 offset:2048
	ds_read_b128 v[178:181], v194 offset:3072
	s_add_u32 s90, s88, 0xfffc0080
	s_addc_u32 s91, s89, -1
	s_cmp_eq_u32 vcc_hi, 12
	s_cselect_b32 s93, s1, s91
	s_cselect_b32 s92, s11, s90
	s_cselect_b32 s91, s79, vcc_lo
	s_cselect_b32 s90, s81, s83
	v_lshl_add_u64 v[190:191], s[88:89], 0, v[156:157]
	s_add_i32 m0, s58, 0xc000
	ds_read_b128 v[182:185], v195
	ds_read_b128 v[186:189], v195 offset:1024
	ds_read_b128 v[200:203], v195 offset:2048
	ds_read_b128 v[204:207], v195 offset:3072
	ds_read_b128 v[208:211], v195 offset:4096
	ds_read_b128 v[212:215], v195 offset:5120
	ds_read_b128 v[216:219], v195 offset:6144
	ds_read_b128 v[220:223], v195 offset:7168
	global_load_lds_dwordx4 v[190:191], off
	v_lshl_add_u64 v[190:191], s[88:89], 0, v[158:159]
	s_add_i32 m0, s58, 0xe000
	s_nop 0
	global_load_lds_dwordx4 v[190:191], off
	s_waitcnt vmcnt(8)
	s_waitcnt lgkmcnt(0)
	s_barrier
	s_waitcnt lgkmcnt(0)
	v_mfma_f32_16x16x32_bf16 v[126:129], v[130:133], v[182:185], v[126:129]
	v_mfma_f32_16x16x32_bf16 v[122:125], v[138:141], v[182:185], v[122:125]
	v_mfma_f32_16x16x32_bf16 v[110:113], v[130:133], v[200:203], v[110:113]
	v_mfma_f32_16x16x32_bf16 v[106:109], v[138:141], v[200:203], v[106:109]
	v_mfma_f32_16x16x32_bf16 v[94:97], v[130:133], v[208:211], v[94:97]
	v_mfma_f32_16x16x32_bf16 v[90:93], v[138:141], v[208:211], v[90:93]
	v_mfma_f32_16x16x32_bf16 v[78:81], v[130:133], v[216:219], v[78:81]
	v_mfma_f32_16x16x32_bf16 v[74:77], v[138:141], v[216:219], v[74:77]
	v_mfma_f32_16x16x32_bf16 v[126:129], v[134:137], v[186:189], v[126:129]
	v_mfma_f32_16x16x32_bf16 v[122:125], v[142:145], v[186:189], v[122:125]
	v_mfma_f32_16x16x32_bf16 v[110:113], v[134:137], v[204:207], v[110:113]
	v_mfma_f32_16x16x32_bf16 v[106:109], v[142:145], v[204:207], v[106:109]
	v_mfma_f32_16x16x32_bf16 v[94:97], v[134:137], v[212:215], v[94:97]
	v_mfma_f32_16x16x32_bf16 v[90:93], v[142:145], v[212:215], v[90:93]
	v_mfma_f32_16x16x32_bf16 v[78:81], v[134:137], v[220:223], v[78:81]
	v_mfma_f32_16x16x32_bf16 v[74:77], v[142:145], v[220:223], v[74:77]
	v_mfma_f32_16x16x32_bf16 v[118:121], v[166:169], v[182:185], v[118:121]
	v_mfma_f32_16x16x32_bf16 v[114:117], v[174:177], v[182:185], v[114:117]
	v_mfma_f32_16x16x32_bf16 v[102:105], v[166:169], v[200:203], v[102:105]
	v_mfma_f32_16x16x32_bf16 v[98:101], v[174:177], v[200:203], v[98:101]
	v_mfma_f32_16x16x32_bf16 v[86:89], v[166:169], v[208:211], v[86:89]
	v_mfma_f32_16x16x32_bf16 v[82:85], v[174:177], v[208:211], v[82:85]
	v_mfma_f32_16x16x32_bf16 v[70:73], v[166:169], v[216:219], v[70:73]
	v_mfma_f32_16x16x32_bf16 v[66:69], v[174:177], v[216:219], v[66:69]
	v_mfma_f32_16x16x32_bf16 v[118:121], v[170:173], v[186:189], v[118:121]
	v_mfma_f32_16x16x32_bf16 v[114:117], v[178:181], v[186:189], v[114:117]
	v_mfma_f32_16x16x32_bf16 v[102:105], v[170:173], v[204:207], v[102:105]
	v_mfma_f32_16x16x32_bf16 v[98:101], v[178:181], v[204:207], v[98:101]
	v_mfma_f32_16x16x32_bf16 v[86:89], v[170:173], v[212:215], v[86:89]
	v_mfma_f32_16x16x32_bf16 v[82:85], v[178:181], v[212:215], v[82:85]
	v_mfma_f32_16x16x32_bf16 v[70:73], v[170:173], v[220:223], v[70:73]
	v_mfma_f32_16x16x32_bf16 v[66:69], v[178:181], v[220:223], v[66:69]
	s_barrier
	s_add_i32 s94, s7, s97
	v_lshl_add_u64 v[190:191], s[90:91], 0, v[148:149]
	s_mov_b32 m0, s94
	ds_read_b128 v[182:185], v195 offset:16384
	ds_read_b128 v[186:189], v195 offset:17408
	ds_read_b128 v[200:203], v195 offset:18432
	ds_read_b128 v[204:207], v195 offset:19456
	ds_read_b128 v[208:211], v195 offset:20480
	ds_read_b128 v[212:215], v195 offset:21504
	ds_read_b128 v[216:219], v195 offset:22528
	ds_read_b128 v[220:223], v195 offset:23552
	global_load_lds_dwordx4 v[190:191], off
	s_add_i32 m0, s94, 0x2000
	s_add_u32 s94, s90, 0x40000
	v_lshl_add_u64 v[224:225], s[90:91], 0, v[152:153]
	s_addc_u32 s95, s91, 0
	s_add_i32 s18, s64, s97
	global_load_lds_dwordx4 v[224:225], off
	v_lshl_add_u64 v[226:227], s[94:95], 0, v[148:149]
	s_mov_b32 m0, s18
	v_lshl_add_u64 v[228:229], s[92:93], 0, v[150:151]
	global_load_lds_dwordx4 v[226:227], off
	v_lshl_add_u64 v[226:227], s[94:95], 0, v[152:153]
	s_add_i32 m0, s18, 0x2000
	s_nop 0
	global_load_lds_dwordx4 v[226:227], off
	v_lshl_add_u64 v[226:227], s[92:93], 0, v[146:147]
	s_mov_b32 m0, s58
	s_nop 0
	global_load_lds_dwordx4 v[226:227], off
	s_mov_b32 m0, s59
	s_nop 0
	global_load_lds_dwordx4 v[228:229], off
	s_waitcnt vmcnt(8)
	s_waitcnt lgkmcnt(0)
	s_barrier
; #define PG8_STAGE(bufoff, gbase, voff) do { _Pragma("unroll") for (int _i = 0; _i < 2; ++_i) \
;         __builtin_amdgcn_global_load_lds((const unsigned*)((const char*)(gbase) + (voff)[_i]), (PG8_LAS unsigned*)(lds + (bufoff) + ldsw + _i * 8192), 16, 0, 0); } while (0)
; #define PG8_LDA(dst, b, h) do { _Pragma("unroll") for (int m = 0; m < 4; ++m) _Pragma("unroll") for (int k = 0; k < 2; ++k) dst[m][k] = *(const PG8_LAS bf16x8*)(lds + PG8_SA(b, h) + aoff + m * 2048 + k * 1024); } while (0)
; #define PG8_LDB(dst, b, h) do { _Pragma("unroll") for (int n = 0; n < 2; ++n) _Pragma("unroll") for (int k = 0; k < 2; ++k) dst[n][k] = *(const PG8_LAS bf16x8*)(lds + PG8_SB(b, h) + boff + n * 2048 + k * 1024); } while (0)
; #define PG8_MMA(ai, bj, At, Bt) do { __builtin_amdgcn_s_setprio(1); _Pragma("unroll") for (int m = 0; m < 4; ++m) _Pragma("unroll") for (int n = 0; n < 2; ++n) _Pragma("unroll") for (int k = 0; k < 2; ++k) \
;         acc[ai][bj][m][n] = __builtin_amdgcn_mfma_f32_16x16x32_bf16(Bt[n][k], At[m][k], acc[ai][bj][m][n], 0, 0, 0); __builtin_amdgcn_s_setprio(0); } while (0)
; #define PG8_WAIT_V(n) asm volatile("s_waitcnt vmcnt(" #n ")" ::: "memory")
; #define PG8_WAIT_L(n) asm volatile("s_waitcnt lgkmcnt(" #n ")" ::: "memory")
; #define PG8_BAR __builtin_amdgcn_s_barrier()
; #define PG8_SCHED __builtin_amdgcn_sched_barrier(0)
; template <class Epi, class Sched, bool ALIGN_EPI = false, bool SP2 = false>
; __device__ __forceinline__ void gemm_phase(PG8_LAS unsigned char* lds, const Gemm g, const Sched& S, const Epi& E) {
;     ...
;             PG8_LDA(At, 0, 1); PG8_STAGE(PG8_SB(0, 0), b2, voffB); PG8_STAGE(PG8_SB(0, 1), b2 + hstep, voffB); PG8_STAGE(PG8_SA(0, 0), a2, voffA);
;             PG8_WAIT_V(8); PG8_WAIT_L(0); PG8_BAR; PG8_MMA(1, 0, At, B0); PG8_MMA(1, 1, At, B1); PG8_BAR; PG8_SCHED;
;             PG8_LDB(B0, 1, 0); PG8_LDB(B1, 1, 1); PG8_SCHED; PG8_LDA(At, 1, 0); PG8_STAGE(PG8_SA(0, 1), a2 + hstep, voffA);
;             PG8_WAIT_V(8); PG8_WAIT_L(0); PG8_BAR; PG8_MMA(0, 0, At, B0); PG8_MMA(0, 1, At, B1); PG8_BAR; PG8_SCHED;
	s_waitcnt lgkmcnt(0)
	v_mfma_f32_16x16x32_bf16 v[62:65], v[130:133], v[182:185], v[62:65]
	v_mfma_f32_16x16x32_bf16 v[58:61], v[138:141], v[182:185], v[58:61]
	v_mfma_f32_16x16x32_bf16 v[46:49], v[130:133], v[200:203], v[46:49]
	v_mfma_f32_16x16x32_bf16 v[42:45], v[138:141], v[200:203], v[42:45]
	v_mfma_f32_16x16x32_bf16 v[30:33], v[130:133], v[208:211], v[30:33]
	v_mfma_f32_16x16x32_bf16 v[26:29], v[138:141], v[208:211], v[26:29]
	v_mfma_f32_16x16x32_bf16 v[14:17], v[130:133], v[216:219], v[14:17]
	v_mfma_f32_16x16x32_bf16 v[10:13], v[138:141], v[216:219], v[10:13]
	v_mfma_f32_16x16x32_bf16 v[62:65], v[134:137], v[186:189], v[62:65]
	v_mfma_f32_16x16x32_bf16 v[58:61], v[142:145], v[186:189], v[58:61]
	v_mfma_f32_16x16x32_bf16 v[46:49], v[134:137], v[204:207], v[46:49]
	v_mfma_f32_16x16x32_bf16 v[42:45], v[142:145], v[204:207], v[42:45]
	v_mfma_f32_16x16x32_bf16 v[30:33], v[134:137], v[212:215], v[30:33]
	v_mfma_f32_16x16x32_bf16 v[26:29], v[142:145], v[212:215], v[26:29]
	v_mfma_f32_16x16x32_bf16 v[14:17], v[134:137], v[220:223], v[14:17]
	v_mfma_f32_16x16x32_bf16 v[10:13], v[142:145], v[220:223], v[10:13]
	v_mfma_f32_16x16x32_bf16 v[54:57], v[166:169], v[182:185], v[54:57]
	v_mfma_f32_16x16x32_bf16 v[50:53], v[174:177], v[182:185], v[50:53]
	v_mfma_f32_16x16x32_bf16 v[38:41], v[166:169], v[200:203], v[38:41]
	v_mfma_f32_16x16x32_bf16 v[34:37], v[174:177], v[200:203], v[34:37]
	v_mfma_f32_16x16x32_bf16 v[22:25], v[166:169], v[208:211], v[22:25]
	v_mfma_f32_16x16x32_bf16 v[18:21], v[174:177], v[208:211], v[18:21]
	v_mfma_f32_16x16x32_bf16 v[6:9], v[166:169], v[216:219], v[6:9]
	v_mfma_f32_16x16x32_bf16 v[2:5], v[174:177], v[216:219], v[2:5]
	v_mfma_f32_16x16x32_bf16 v[54:57], v[170:173], v[186:189], v[54:57]
	v_mfma_f32_16x16x32_bf16 v[50:53], v[178:181], v[186:189], v[50:53]
	v_mfma_f32_16x16x32_bf16 v[38:41], v[170:173], v[204:207], v[38:41]
	v_mfma_f32_16x16x32_bf16 v[34:37], v[178:181], v[204:207], v[34:37]
	v_mfma_f32_16x16x32_bf16 v[22:25], v[170:173], v[212:215], v[22:25]
	v_mfma_f32_16x16x32_bf16 v[18:21], v[178:181], v[212:215], v[18:21]
	v_mfma_f32_16x16x32_bf16 v[6:9], v[170:173], v[220:223], v[6:9]
	v_mfma_f32_16x16x32_bf16 v[2:5], v[178:181], v[220:223], v[2:5]
	s_barrier
	s_add_i32 s18, 0, 0x18000
	s_add_i32 s94, 0, 0x1c000
	v_add_u32_e32 v142, s18, v192
	v_add_u32_e32 v154, s94, v192
	ds_read_b128 v[130:133], v142
	ds_read_b128 v[134:137], v142 offset:1024
	ds_read_b128 v[138:141], v142 offset:2048
	ds_read_b128 v[142:145], v142 offset:3072
	ds_read_b128 v[166:169], v154
	ds_read_b128 v[170:173], v154 offset:1024
	ds_read_b128 v[174:177], v154 offset:2048
	ds_read_b128 v[178:181], v154 offset:3072
	s_add_u32 s92, s92, 0x40000
	s_addc_u32 s93, s93, 0
	s_mov_b32 m0, s56
	v_lshl_add_u64 v[230:231], s[92:93], 0, v[146:147]
	ds_read_b128 v[182:185], v195 offset:32768
	ds_read_b128 v[186:189], v195 offset:33792
	ds_read_b128 v[200:203], v195 offset:34816
	ds_read_b128 v[204:207], v195 offset:35840
	ds_read_b128 v[208:211], v195 offset:36864
	ds_read_b128 v[212:215], v195 offset:37888
	ds_read_b128 v[216:219], v195 offset:38912
	ds_read_b128 v[220:223], v195 offset:39936
	global_load_lds_dwordx4 v[230:231], off
	v_lshl_add_u64 v[230:231], s[92:93], 0, v[150:151]
	s_mov_b32 m0, s57
	s_nop 0
	global_load_lds_dwordx4 v[230:231], off
	s_waitcnt vmcnt(8)
	s_waitcnt lgkmcnt(0)
	s_barrier
	s_waitcnt lgkmcnt(0)
	v_mfma_f32_16x16x32_bf16 v[126:129], v[130:133], v[182:185], v[126:129]
	v_mfma_f32_16x16x32_bf16 v[122:125], v[138:141], v[182:185], v[122:125]
	v_mfma_f32_16x16x32_bf16 v[110:113], v[130:133], v[200:203], v[110:113]
	v_mfma_f32_16x16x32_bf16 v[106:109], v[138:141], v[200:203], v[106:109]
	v_mfma_f32_16x16x32_bf16 v[94:97], v[130:133], v[208:211], v[94:97]
	v_mfma_f32_16x16x32_bf16 v[90:93], v[138:141], v[208:211], v[90:93]
	v_mfma_f32_16x16x32_bf16 v[78:81], v[130:133], v[216:219], v[78:81]
	v_mfma_f32_16x16x32_bf16 v[74:77], v[138:141], v[216:219], v[74:77]
	v_mfma_f32_16x16x32_bf16 v[126:129], v[134:137], v[186:189], v[126:129]
	v_mfma_f32_16x16x32_bf16 v[122:125], v[142:145], v[186:189], v[122:125]
	v_mfma_f32_16x16x32_bf16 v[110:113], v[134:137], v[204:207], v[110:113]
	v_mfma_f32_16x16x32_bf16 v[106:109], v[142:145], v[204:207], v[106:109]
	v_mfma_f32_16x16x32_bf16 v[94:97], v[134:137], v[212:215], v[94:97]
	v_mfma_f32_16x16x32_bf16 v[90:93], v[142:145], v[212:215], v[90:93]
	v_mfma_f32_16x16x32_bf16 v[78:81], v[134:137], v[220:223], v[78:81]
	v_mfma_f32_16x16x32_bf16 v[74:77], v[142:145], v[220:223], v[74:77]
	v_mfma_f32_16x16x32_bf16 v[118:121], v[166:169], v[182:185], v[118:121]
	v_mfma_f32_16x16x32_bf16 v[114:117], v[174:177], v[182:185], v[114:117]
	v_mfma_f32_16x16x32_bf16 v[102:105], v[166:169], v[200:203], v[102:105]
	v_mfma_f32_16x16x32_bf16 v[98:101], v[174:177], v[200:203], v[98:101]
	v_mfma_f32_16x16x32_bf16 v[86:89], v[166:169], v[208:211], v[86:89]
	v_mfma_f32_16x16x32_bf16 v[82:85], v[174:177], v[208:211], v[82:85]
	v_mfma_f32_16x16x32_bf16 v[70:73], v[166:169], v[216:219], v[70:73]
	v_mfma_f32_16x16x32_bf16 v[66:69], v[174:177], v[216:219], v[66:69]
	v_mfma_f32_16x16x32_bf16 v[118:121], v[170:173], v[186:189], v[118:121]
	v_mfma_f32_16x16x32_bf16 v[114:117], v[178:181], v[186:189], v[114:117]
	v_mfma_f32_16x16x32_bf16 v[102:105], v[170:173], v[204:207], v[102:105]
	v_mfma_f32_16x16x32_bf16 v[98:101], v[178:181], v[204:207], v[98:101]
	v_mfma_f32_16x16x32_bf16 v[86:89], v[170:173], v[212:215], v[86:89]
	v_mfma_f32_16x16x32_bf16 v[82:85], v[178:181], v[212:215], v[82:85]
	v_mfma_f32_16x16x32_bf16 v[70:73], v[170:173], v[220:223], v[70:73]
	v_mfma_f32_16x16x32_bf16 v[66:69], v[178:181], v[220:223], v[66:69]
	s_barrier
; #define PG8_STAGE(bufoff, gbase, voff) do { _Pragma("unroll") for (int _i = 0; _i < 2; ++_i) \
;         __builtin_amdgcn_global_load_lds((const unsigned*)((const char*)(gbase) + (voff)[_i]), (PG8_LAS unsigned*)(lds + (bufoff) + ldsw + _i * 8192), 16, 0, 0); } while (0)
; #define PG8_LDA(dst, b, h) do { _Pragma("unroll") for (int m = 0; m < 4; ++m) _Pragma("unroll") for (int k = 0; k < 2; ++k) dst[m][k] = *(const PG8_LAS bf16x8*)(lds + PG8_SA(b, h) + aoff + m * 2048 + k * 1024); } while (0)
; #define PG8_MMA(ai, bj, At, Bt) do { __builtin_amdgcn_s_setprio(1); _Pragma("unroll") for (int m = 0; m < 4; ++m) _Pragma("unroll") for (int n = 0; n < 2; ++n) _Pragma("unroll") for (int k = 0; k < 2; ++k) \
;         acc[ai][bj][m][n] = __builtin_amdgcn_mfma_f32_16x16x32_bf16(Bt[n][k], At[m][k], acc[ai][bj][m][n], 0, 0, 0); __builtin_amdgcn_s_setprio(0); } while (0)
; #define PG8_WAIT_V(n) asm volatile("s_waitcnt vmcnt(" #n ")" ::: "memory")
; #define PG8_WAIT_L(n) asm volatile("s_waitcnt lgkmcnt(" #n ")" ::: "memory")
; #define PG8_BAR __builtin_amdgcn_s_barrier()
; #define PG8_SCHED __builtin_amdgcn_sched_barrier(0)
; template <class Epi, class Sched, bool ALIGN_EPI = false, bool SP2 = false>
; __device__ __forceinline__ void gemm_phase(PG8_LAS unsigned char* lds, const Gemm g, const Sched& S, const Epi& E) {
;     ...
;             PG8_WAIT_V(8); PG8_WAIT_L(0); PG8_BAR; PG8_MMA(0, 0, At, B0); PG8_MMA(0, 1, At, B1); PG8_BAR; PG8_SCHED;
;             PG8_LDA(At, 1, 1); PG8_STAGE(PG8_SB(1, 0), b3, voffB); PG8_STAGE(PG8_SB(1, 1), b3 + hstep, voffB); PG8_STAGE(PG8_SA(1, 0), a3, voffA);
;             PG8_WAIT_V(8); PG8_WAIT_L(0); PG8_BAR; PG8_MMA(1, 0, At, B0); PG8_MMA(1, 1, At, B1); PG8_BAR; PG8_SCHED;
	s_add_i32 s18, s18, s97
	v_lshl_add_u64 v[190:191], v[190:191], 0, s[74:75]
	s_mov_b32 m0, s18
	ds_read_b128 v[182:185], v195 offset:49152
	ds_read_b128 v[186:189], v195 offset:50176
	ds_read_b128 v[200:203], v195 offset:51200
	ds_read_b128 v[204:207], v195 offset:52224
	ds_read_b128 v[208:211], v195 offset:53248
	ds_read_b128 v[212:215], v195 offset:54272
	ds_read_b128 v[216:219], v195 offset:55296
	ds_read_b128 v[220:223], v195 offset:56320
	global_load_lds_dwordx4 v[190:191], off
	s_add_i32 m0, s18, 0x2000
	s_add_u32 s90, s90, 0x40080
	v_lshl_add_u64 v[190:191], v[224:225], 0, s[74:75]
	s_addc_u32 s91, s91, 0
	s_add_i32 s18, s94, s97
	global_load_lds_dwordx4 v[190:191], off
	v_lshl_add_u64 v[190:191], s[90:91], 0, v[148:149]
	s_mov_b32 m0, s18
	s_nop 0
	global_load_lds_dwordx4 v[190:191], off
	v_lshl_add_u64 v[190:191], s[90:91], 0, v[152:153]
	s_add_i32 m0, s18, 0x2000
	s_nop 0
	global_load_lds_dwordx4 v[190:191], off
	v_lshl_add_u64 v[190:191], v[226:227], 0, s[74:75]
	s_mov_b32 m0, s19
	s_nop 0
	global_load_lds_dwordx4 v[190:191], off
	v_lshl_add_u64 v[190:191], v[228:229], 0, s[74:75]
	s_mov_b32 m0, s66
	s_nop 0
	global_load_lds_dwordx4 v[190:191], off
	s_waitcnt vmcnt(8)
	s_waitcnt lgkmcnt(0)
	s_barrier
	s_waitcnt lgkmcnt(0)
	v_mfma_f32_16x16x32_bf16 v[62:65], v[130:133], v[182:185], v[62:65]
	v_mfma_f32_16x16x32_bf16 v[58:61], v[138:141], v[182:185], v[58:61]
	v_mfma_f32_16x16x32_bf16 v[46:49], v[130:133], v[200:203], v[46:49]
	v_mfma_f32_16x16x32_bf16 v[42:45], v[138:141], v[200:203], v[42:45]
	v_mfma_f32_16x16x32_bf16 v[30:33], v[130:133], v[208:211], v[30:33]
	v_mfma_f32_16x16x32_bf16 v[26:29], v[138:141], v[208:211], v[26:29]
	v_mfma_f32_16x16x32_bf16 v[14:17], v[130:133], v[216:219], v[14:17]
	v_mfma_f32_16x16x32_bf16 v[10:13], v[138:141], v[216:219], v[10:13]
	v_mfma_f32_16x16x32_bf16 v[62:65], v[134:137], v[186:189], v[62:65]
	v_mfma_f32_16x16x32_bf16 v[58:61], v[142:145], v[186:189], v[58:61]
	v_mfma_f32_16x16x32_bf16 v[46:49], v[134:137], v[204:207], v[46:49]
	v_mfma_f32_16x16x32_bf16 v[42:45], v[142:145], v[204:207], v[42:45]
	v_mfma_f32_16x16x32_bf16 v[30:33], v[134:137], v[212:215], v[30:33]
	v_mfma_f32_16x16x32_bf16 v[26:29], v[142:145], v[212:215], v[26:29]
	v_mfma_f32_16x16x32_bf16 v[14:17], v[134:137], v[220:223], v[14:17]
	v_mfma_f32_16x16x32_bf16 v[10:13], v[142:145], v[220:223], v[10:13]
	v_mfma_f32_16x16x32_bf16 v[54:57], v[166:169], v[182:185], v[54:57]
	v_mfma_f32_16x16x32_bf16 v[50:53], v[174:177], v[182:185], v[50:53]
	v_mfma_f32_16x16x32_bf16 v[38:41], v[166:169], v[200:203], v[38:41]
	v_mfma_f32_16x16x32_bf16 v[34:37], v[174:177], v[200:203], v[34:37]
	v_mfma_f32_16x16x32_bf16 v[22:25], v[166:169], v[208:211], v[22:25]
	v_mfma_f32_16x16x32_bf16 v[18:21], v[174:177], v[208:211], v[18:21]
	v_mfma_f32_16x16x32_bf16 v[6:9], v[166:169], v[216:219], v[6:9]
	v_mfma_f32_16x16x32_bf16 v[2:5], v[174:177], v[216:219], v[2:5]
	v_mfma_f32_16x16x32_bf16 v[54:57], v[170:173], v[186:189], v[54:57]
	v_mfma_f32_16x16x32_bf16 v[50:53], v[178:181], v[186:189], v[50:53]
	v_mfma_f32_16x16x32_bf16 v[38:41], v[170:173], v[204:207], v[38:41]
	v_mfma_f32_16x16x32_bf16 v[34:37], v[178:181], v[204:207], v[34:37]
	v_mfma_f32_16x16x32_bf16 v[22:25], v[170:173], v[212:215], v[22:25]
	v_mfma_f32_16x16x32_bf16 v[18:21], v[178:181], v[212:215], v[18:21]
	v_mfma_f32_16x16x32_bf16 v[6:9], v[170:173], v[220:223], v[6:9]
	v_mfma_f32_16x16x32_bf16 v[2:5], v[178:181], v[220:223], v[2:5]
	s_barrier
	s_add_i32 vcc_hi, vcc_hi, 2
	s_add_u32 s88, s88, 0x100
	s_addc_u32 s89, s89, 0
	s_add_u32 s83, s83, 0x100
	s_addc_u32 vcc_lo, vcc_lo, 0
	s_cmp_gt_u32 vcc_hi, 13
	s_cbranch_scc0 .LBB0_143
	s_and_b64 vcc, exec, s[76:77]
	s_cbranch_vccz .LBB0_146
	s_barrier

; #define PG8_STAGE(bufoff, gbase, voff) do { _Pragma("unroll") for (int _i = 0; _i < 2; ++_i) \
;         __builtin_amdgcn_global_load_lds((const unsigned*)((const char*)(gbase) + (voff)[_i]), (PG8_LAS unsigned*)(lds + (bufoff) + ldsw + _i * 8192), 16, 0, 0); } while (0)
; #define PG8_LDA(dst, b, h) do { _Pragma("unroll") for (int m = 0; m < 4; ++m) _Pragma("unroll") for (int k = 0; k < 2; ++k) dst[m][k] = *(const PG8_LAS bf16x8*)(lds + PG8_SA(b, h) + aoff + m * 2048 + k * 1024); } while (0)
; #define PG8_LDB(dst, b, h) do { _Pragma("unroll") for (int n = 0; n < 2; ++n) _Pragma("unroll") for (int k = 0; k < 2; ++k) dst[n][k] = *(const PG8_LAS bf16x8*)(lds + PG8_SB(b, h) + boff + n * 2048 + k * 1024); } while (0)
; #define PG8_MMA(ai, bj, At, Bt) do { __builtin_amdgcn_s_setprio(1); _Pragma("unroll") for (int m = 0; m < 4; ++m) _Pragma("unroll") for (int n = 0; n < 2; ++n) _Pragma("unroll") for (int k = 0; k < 2; ++k) \
;         acc[ai][bj][m][n] = __builtin_amdgcn_mfma_f32_16x16x32_bf16(Bt[n][k], At[m][k], acc[ai][bj][m][n], 0, 0, 0); __builtin_amdgcn_s_setprio(0); } while (0)
; #define PG8_WAIT_V(n) asm volatile("s_waitcnt vmcnt(" #n ")" ::: "memory")
; #define PG8_WAIT_L(n) asm volatile("s_waitcnt lgkmcnt(" #n ")" ::: "memory")
; #define PG8_BAR __builtin_amdgcn_s_barrier()
; #define PG8_SCHED __builtin_amdgcn_sched_barrier(0)
; template <class Epi, class Sched, bool ALIGN_EPI = false, bool SP2 = false>
; __device__ __forceinline__ void gemm_phase(PG8_LAS unsigned char* lds, const Gemm g, const Sched& S, const Epi& E) {
;     ...
;             PG8_LDB(B0, 0, 0); PG8_LDB(B1, 0, 1); PG8_SCHED; PG8_LDA(At, 0, 0); PG8_STAGE(PG8_SA(1, 1), a1 + hstep, voffA);
;             PG8_WAIT_V(8); PG8_WAIT_L(0); PG8_BAR; PG8_MMA(0, 0, At, B0); PG8_MMA(0, 1, At, B1); PG8_BAR; PG8_SCHED;
;             PG8_LDA(At, 0, 1); PG8_STAGE(PG8_SB(0, 0), b2, voffB); PG8_STAGE(PG8_SB(0, 1), b2 + hstep, voffB); PG8_STAGE(PG8_SA(0, 0), a2, voffA);
;             PG8_WAIT_V(8); PG8_WAIT_L(0); PG8_BAR; PG8_MMA(1, 0, At, B0); PG8_MMA(1, 1, At, B1); PG8_BAR; PG8_SCHED;
.LBB0_587:
	s_add_u32 s2, s46, s60
	s_addc_u32 s62, s47, s61
	s_add_u32 s2, s2, 0x100
	s_addc_u32 s62, s62, 0
	s_add_u32 s95, s92, s60
	s_addc_u32 s63, s93, s61
	s_add_i32 s96, 0, 0x10000
	v_add_u32_e32 v3, s96, v209
	ds_read_b128 v[134:137], v3
	ds_read_b128 v[138:141], v3 offset:1024
	ds_read_b128 v[142:145], v3 offset:2048
	ds_read_b128 v[146:149], v3 offset:3072
	v_add_u32_e32 v3, s88, v209
	ds_read_b128 v[150:153], v3
	ds_read_b128 v[154:157], v3 offset:1024
	ds_read_b128 v[158:161], v3 offset:2048
	ds_read_b128 v[162:165], v3 offset:3072
	s_cmpk_eq_i32 s60, 0x700
	s_cselect_b32 s65, s29, s62
	s_cselect_b32 s64, s90, s2
	s_cselect_b32 s63, s31, s63
	s_cselect_b32 s62, s91, s95
	v_lshl_add_u64 v[4:5], v[204:205], 0, s[60:61]
	s_add_i32 m0, s59, 0xc000
	ds_read_b128 v[166:169], v210
	ds_read_b128 v[170:173], v210 offset:1024
	ds_read_b128 v[174:177], v210 offset:2048
	ds_read_b128 v[178:181], v210 offset:3072
	ds_read_b128 v[182:185], v210 offset:4096
	ds_read_b128 v[186:189], v210 offset:5120
	ds_read_b128 v[212:215], v210 offset:6144
	ds_read_b128 v[216:219], v210 offset:7168
	global_load_lds_dwordx4 v[4:5], off
	v_lshl_add_u64 v[4:5], v[206:207], 0, s[60:61]
	s_add_i32 m0, s59, 0xe000
	s_nop 0
	global_load_lds_dwordx4 v[4:5], off
	s_waitcnt vmcnt(8)
	s_waitcnt lgkmcnt(0)
	s_barrier
	s_waitcnt lgkmcnt(0)
	v_mfma_f32_16x16x32_bf16 v[130:133], v[134:137], v[166:169], v[130:133]
	v_mfma_f32_16x16x32_bf16 v[126:129], v[142:145], v[166:169], v[126:129]
	v_mfma_f32_16x16x32_bf16 v[114:117], v[134:137], v[174:177], v[114:117]
	v_mfma_f32_16x16x32_bf16 v[110:113], v[142:145], v[174:177], v[110:113]
	v_mfma_f32_16x16x32_bf16 v[98:101], v[134:137], v[182:185], v[98:101]
	v_mfma_f32_16x16x32_bf16 v[94:97], v[142:145], v[182:185], v[94:97]
	v_mfma_f32_16x16x32_bf16 v[82:85], v[134:137], v[212:215], v[82:85]
	v_mfma_f32_16x16x32_bf16 v[78:81], v[142:145], v[212:215], v[78:81]
	v_mfma_f32_16x16x32_bf16 v[130:133], v[138:141], v[170:173], v[130:133]
	v_mfma_f32_16x16x32_bf16 v[126:129], v[146:149], v[170:173], v[126:129]
	v_mfma_f32_16x16x32_bf16 v[114:117], v[138:141], v[178:181], v[114:117]
	v_mfma_f32_16x16x32_bf16 v[110:113], v[146:149], v[178:181], v[110:113]
	v_mfma_f32_16x16x32_bf16 v[98:101], v[138:141], v[186:189], v[98:101]
	v_mfma_f32_16x16x32_bf16 v[94:97], v[146:149], v[186:189], v[94:97]
	v_mfma_f32_16x16x32_bf16 v[82:85], v[138:141], v[216:219], v[82:85]
	v_mfma_f32_16x16x32_bf16 v[78:81], v[146:149], v[216:219], v[78:81]
	v_mfma_f32_16x16x32_bf16 v[122:125], v[150:153], v[166:169], v[122:125]
	v_mfma_f32_16x16x32_bf16 v[118:121], v[158:161], v[166:169], v[118:121]
	v_mfma_f32_16x16x32_bf16 v[106:109], v[150:153], v[174:177], v[106:109]
	v_mfma_f32_16x16x32_bf16 v[102:105], v[158:161], v[174:177], v[102:105]
	v_mfma_f32_16x16x32_bf16 v[90:93], v[150:153], v[182:185], v[90:93]
	v_mfma_f32_16x16x32_bf16 v[86:89], v[158:161], v[182:185], v[86:89]
	v_mfma_f32_16x16x32_bf16 v[74:77], v[150:153], v[212:215], v[74:77]
	v_mfma_f32_16x16x32_bf16 v[70:73], v[158:161], v[212:215], v[70:73]
	v_mfma_f32_16x16x32_bf16 v[122:125], v[154:157], v[170:173], v[122:125]
	v_mfma_f32_16x16x32_bf16 v[118:121], v[162:165], v[170:173], v[118:121]
	v_mfma_f32_16x16x32_bf16 v[106:109], v[154:157], v[178:181], v[106:109]
	v_mfma_f32_16x16x32_bf16 v[102:105], v[162:165], v[178:181], v[102:105]
	v_mfma_f32_16x16x32_bf16 v[90:93], v[154:157], v[186:189], v[90:93]
	v_mfma_f32_16x16x32_bf16 v[86:89], v[162:165], v[186:189], v[86:89]
	v_mfma_f32_16x16x32_bf16 v[74:77], v[154:157], v[216:219], v[74:77]
	v_mfma_f32_16x16x32_bf16 v[70:73], v[162:165], v[216:219], v[70:73]
	s_barrier
	s_add_i32 s2, s96, s58
	v_lshl_add_u64 v[220:221], s[62:63], 0, v[192:193]
	s_mov_b32 m0, s2
	ds_read_b128 v[166:169], v210 offset:16384
	ds_read_b128 v[170:173], v210 offset:17408
	ds_read_b128 v[174:177], v210 offset:18432
	ds_read_b128 v[178:181], v210 offset:19456
	ds_read_b128 v[182:185], v210 offset:20480
	ds_read_b128 v[186:189], v210 offset:21504
	ds_read_b128 v[212:215], v210 offset:22528
	ds_read_b128 v[216:219], v210 offset:23552
	global_load_lds_dwordx4 v[220:221], off
	s_add_i32 m0, s2, 0x2000
	s_add_u32 s96, s62, 0x40000
	v_lshl_add_u64 v[222:223], s[62:63], 0, v[196:197]
	s_addc_u32 s97, s63, 0
	s_add_i32 s2, s88, s58
	global_load_lds_dwordx4 v[222:223], off
	v_lshl_add_u64 v[4:5], s[96:97], 0, v[192:193]
	s_mov_b32 m0, s2
	v_lshl_add_u64 v[224:225], s[64:65], 0, v[190:191]
	global_load_lds_dwordx4 v[4:5], off
	v_lshl_add_u64 v[4:5], s[96:97], 0, v[196:197]
	s_add_i32 m0, s2, 0x2000
	v_lshl_add_u64 v[226:227], s[64:65], 0, v[194:195]
	global_load_lds_dwordx4 v[4:5], off
	s_mov_b32 m0, s59
	s_nop 0
	global_load_lds_dwordx4 v[224:225], off
	s_mov_b32 m0, s66
	s_nop 0
	global_load_lds_dwordx4 v[226:227], off
	s_waitcnt vmcnt(8)
	s_waitcnt lgkmcnt(0)
	s_barrier
; #define PG8_STAGE(bufoff, gbase, voff) do { _Pragma("unroll") for (int _i = 0; _i < 2; ++_i) \
;         __builtin_amdgcn_global_load_lds((const unsigned*)((const char*)(gbase) + (voff)[_i]), (PG8_LAS unsigned*)(lds + (bufoff) + ldsw + _i * 8192), 16, 0, 0); } while (0)
; #define PG8_LDA(dst, b, h) do { _Pragma("unroll") for (int m = 0; m < 4; ++m) _Pragma("unroll") for (int k = 0; k < 2; ++k) dst[m][k] = *(const PG8_LAS bf16x8*)(lds + PG8_SA(b, h) + aoff + m * 2048 + k * 1024); } while (0)
; #define PG8_LDB(dst, b, h) do { _Pragma("unroll") for (int n = 0; n < 2; ++n) _Pragma("unroll") for (int k = 0; k < 2; ++k) dst[n][k] = *(const PG8_LAS bf16x8*)(lds + PG8_SB(b, h) + boff + n * 2048 + k * 1024); } while (0)
; #define PG8_MMA(ai, bj, At, Bt) do { __builtin_amdgcn_s_setprio(1); _Pragma("unroll") for (int m = 0; m < 4; ++m) _Pragma("unroll") for (int n = 0; n < 2; ++n) _Pragma("unroll") for (int k = 0; k < 2; ++k) \
;         acc[ai][bj][m][n] = __builtin_amdgcn_mfma_f32_16x16x32_bf16(Bt[n][k], At[m][k], acc[ai][bj][m][n], 0, 0, 0); __builtin_amdgcn_s_setprio(0); } while (0)
; #define PG8_WAIT_V(n) asm volatile("s_waitcnt vmcnt(" #n ")" ::: "memory")
; #define PG8_WAIT_L(n) asm volatile("s_waitcnt lgkmcnt(" #n ")" ::: "memory")
; #define PG8_BAR __builtin_amdgcn_s_barrier()
; #define PG8_SCHED __builtin_amdgcn_sched_barrier(0)
; template <class Epi, class Sched, bool ALIGN_EPI = false, bool SP2 = false>
; __device__ __forceinline__ void gemm_phase(PG8_LAS unsigned char* lds, const Gemm g, const Sched& S, const Epi& E) {
;     ...
;             PG8_LDA(At, 0, 1); PG8_STAGE(PG8_SB(0, 0), b2, voffB); PG8_STAGE(PG8_SB(0, 1), b2 + hstep, voffB); PG8_STAGE(PG8_SA(0, 0), a2, voffA);
;             PG8_WAIT_V(8); PG8_WAIT_L(0); PG8_BAR; PG8_MMA(1, 0, At, B0); PG8_MMA(1, 1, At, B1); PG8_BAR; PG8_SCHED;
;             PG8_LDB(B0, 1, 0); PG8_LDB(B1, 1, 1); PG8_SCHED; PG8_LDA(At, 1, 0); PG8_STAGE(PG8_SA(0, 1), a2 + hstep, voffA);
;             PG8_WAIT_V(8); PG8_WAIT_L(0); PG8_BAR; PG8_MMA(0, 0, At, B0); PG8_MMA(0, 1, At, B1); PG8_BAR; PG8_SCHED;
	s_waitcnt lgkmcnt(0)
	v_mfma_f32_16x16x32_bf16 v[66:69], v[134:137], v[166:169], v[66:69]
	v_mfma_f32_16x16x32_bf16 v[62:65], v[142:145], v[166:169], v[62:65]
	v_mfma_f32_16x16x32_bf16 v[50:53], v[134:137], v[174:177], v[50:53]
	v_mfma_f32_16x16x32_bf16 v[46:49], v[142:145], v[174:177], v[46:49]
	v_mfma_f32_16x16x32_bf16 v[34:37], v[134:137], v[182:185], v[34:37]
	v_mfma_f32_16x16x32_bf16 v[30:33], v[142:145], v[182:185], v[30:33]
	v_mfma_f32_16x16x32_bf16 v[18:21], v[134:137], v[212:215], v[18:21]
	v_mfma_f32_16x16x32_bf16 v[14:17], v[142:145], v[212:215], v[14:17]
	v_mfma_f32_16x16x32_bf16 v[66:69], v[138:141], v[170:173], v[66:69]
	v_mfma_f32_16x16x32_bf16 v[62:65], v[146:149], v[170:173], v[62:65]
	v_mfma_f32_16x16x32_bf16 v[50:53], v[138:141], v[178:181], v[50:53]
	v_mfma_f32_16x16x32_bf16 v[46:49], v[146:149], v[178:181], v[46:49]
	v_mfma_f32_16x16x32_bf16 v[34:37], v[138:141], v[186:189], v[34:37]
	v_mfma_f32_16x16x32_bf16 v[30:33], v[146:149], v[186:189], v[30:33]
	v_mfma_f32_16x16x32_bf16 v[18:21], v[138:141], v[216:219], v[18:21]
	v_mfma_f32_16x16x32_bf16 v[14:17], v[146:149], v[216:219], v[14:17]
	v_mfma_f32_16x16x32_bf16 v[58:61], v[150:153], v[166:169], v[58:61]
	v_mfma_f32_16x16x32_bf16 v[54:57], v[158:161], v[166:169], v[54:57]
	v_mfma_f32_16x16x32_bf16 v[42:45], v[150:153], v[174:177], v[42:45]
	v_mfma_f32_16x16x32_bf16 v[38:41], v[158:161], v[174:177], v[38:41]
	v_mfma_f32_16x16x32_bf16 v[26:29], v[150:153], v[182:185], v[26:29]
	v_mfma_f32_16x16x32_bf16 v[22:25], v[158:161], v[182:185], v[22:25]
	v_mfma_f32_16x16x32_bf16 v[10:13], v[150:153], v[212:215], v[10:13]
	v_mfma_f32_16x16x32_bf16 v[4:7], v[158:161], v[212:215], v[6:9]
	v_mfma_f32_16x16x32_bf16 v[58:61], v[154:157], v[170:173], v[58:61]
	v_mfma_f32_16x16x32_bf16 v[54:57], v[162:165], v[170:173], v[54:57]
	v_mfma_f32_16x16x32_bf16 v[42:45], v[154:157], v[178:181], v[42:45]
	v_mfma_f32_16x16x32_bf16 v[38:41], v[162:165], v[178:181], v[38:41]
	v_mfma_f32_16x16x32_bf16 v[26:29], v[154:157], v[186:189], v[26:29]
	v_mfma_f32_16x16x32_bf16 v[22:25], v[162:165], v[186:189], v[22:25]
	v_mfma_f32_16x16x32_bf16 v[10:13], v[154:157], v[216:219], v[10:13]
	v_mfma_f32_16x16x32_bf16 v[4:7], v[162:165], v[216:219], v[4:7]
	s_barrier
	s_add_i32 s2, 0, 0x18000
	v_add_u32_e32 v3, s2, v209
	s_add_i32 s95, 0, 0x1c000
	ds_read_b128 v[134:137], v3
	ds_read_b128 v[138:141], v3 offset:1024
	ds_read_b128 v[142:145], v3 offset:2048
	ds_read_b128 v[146:149], v3 offset:3072
	v_add_u32_e32 v3, s95, v209
	ds_read_b128 v[150:153], v3
	ds_read_b128 v[154:157], v3 offset:1024
	ds_read_b128 v[158:161], v3 offset:2048
	ds_read_b128 v[162:165], v3 offset:3072
	s_add_u32 s64, s64, 0x40000
	s_addc_u32 s65, s65, 0
	s_mov_b32 m0, s67
	v_lshl_add_u64 v[8:9], s[64:65], 0, v[190:191]
	ds_read_b128 v[166:169], v210 offset:32768
	ds_read_b128 v[170:173], v210 offset:33792
	ds_read_b128 v[174:177], v210 offset:34816
	ds_read_b128 v[178:181], v210 offset:35840
	ds_read_b128 v[182:185], v210 offset:36864
	ds_read_b128 v[186:189], v210 offset:37888
	ds_read_b128 v[212:215], v210 offset:38912
	ds_read_b128 v[216:219], v210 offset:39936
	global_load_lds_dwordx4 v[8:9], off
	v_lshl_add_u64 v[8:9], s[64:65], 0, v[194:195]
	s_mov_b32 m0, s68
	s_nop 0
	global_load_lds_dwordx4 v[8:9], off
	s_waitcnt vmcnt(8)
	s_waitcnt lgkmcnt(0)
	s_barrier
	s_waitcnt lgkmcnt(0)
	v_mfma_f32_16x16x32_bf16 v[130:133], v[134:137], v[166:169], v[130:133]
	v_mfma_f32_16x16x32_bf16 v[126:129], v[142:145], v[166:169], v[126:129]
	v_mfma_f32_16x16x32_bf16 v[114:117], v[134:137], v[174:177], v[114:117]
	v_mfma_f32_16x16x32_bf16 v[110:113], v[142:145], v[174:177], v[110:113]
	v_mfma_f32_16x16x32_bf16 v[98:101], v[134:137], v[182:185], v[98:101]
	v_mfma_f32_16x16x32_bf16 v[94:97], v[142:145], v[182:185], v[94:97]
	v_mfma_f32_16x16x32_bf16 v[82:85], v[134:137], v[212:215], v[82:85]
	v_mfma_f32_16x16x32_bf16 v[78:81], v[142:145], v[212:215], v[78:81]
	v_mfma_f32_16x16x32_bf16 v[130:133], v[138:141], v[170:173], v[130:133]
	v_mfma_f32_16x16x32_bf16 v[126:129], v[146:149], v[170:173], v[126:129]
	v_mfma_f32_16x16x32_bf16 v[114:117], v[138:141], v[178:181], v[114:117]
	v_mfma_f32_16x16x32_bf16 v[110:113], v[146:149], v[178:181], v[110:113]
	v_mfma_f32_16x16x32_bf16 v[98:101], v[138:141], v[186:189], v[98:101]
	v_mfma_f32_16x16x32_bf16 v[94:97], v[146:149], v[186:189], v[94:97]
	v_mfma_f32_16x16x32_bf16 v[82:85], v[138:141], v[216:219], v[82:85]
	v_mfma_f32_16x16x32_bf16 v[78:81], v[146:149], v[216:219], v[78:81]
	v_mfma_f32_16x16x32_bf16 v[122:125], v[150:153], v[166:169], v[122:125]
	v_mfma_f32_16x16x32_bf16 v[118:121], v[158:161], v[166:169], v[118:121]
	v_mfma_f32_16x16x32_bf16 v[106:109], v[150:153], v[174:177], v[106:109]
	v_mfma_f32_16x16x32_bf16 v[102:105], v[158:161], v[174:177], v[102:105]
	v_mfma_f32_16x16x32_bf16 v[90:93], v[150:153], v[182:185], v[90:93]
	v_mfma_f32_16x16x32_bf16 v[86:89], v[158:161], v[182:185], v[86:89]
	v_mfma_f32_16x16x32_bf16 v[74:77], v[150:153], v[212:215], v[74:77]
	v_mfma_f32_16x16x32_bf16 v[70:73], v[158:161], v[212:215], v[70:73]
	v_mfma_f32_16x16x32_bf16 v[122:125], v[154:157], v[170:173], v[122:125]
	v_mfma_f32_16x16x32_bf16 v[118:121], v[162:165], v[170:173], v[118:121]
	v_mfma_f32_16x16x32_bf16 v[106:109], v[154:157], v[178:181], v[106:109]
	v_mfma_f32_16x16x32_bf16 v[102:105], v[162:165], v[178:181], v[102:105]
	v_mfma_f32_16x16x32_bf16 v[90:93], v[154:157], v[186:189], v[90:93]
	v_mfma_f32_16x16x32_bf16 v[86:89], v[162:165], v[186:189], v[86:89]
	v_mfma_f32_16x16x32_bf16 v[74:77], v[154:157], v[216:219], v[74:77]
	v_mfma_f32_16x16x32_bf16 v[70:73], v[162:165], v[216:219], v[70:73]
	s_barrier
; #define PG8_STAGE(bufoff, gbase, voff) do { _Pragma("unroll") for (int _i = 0; _i < 2; ++_i) \
;         __builtin_amdgcn_global_load_lds((const unsigned*)((const char*)(gbase) + (voff)[_i]), (PG8_LAS unsigned*)(lds + (bufoff) + ldsw + _i * 8192), 16, 0, 0); } while (0)
; #define PG8_LDA(dst, b, h) do { _Pragma("unroll") for (int m = 0; m < 4; ++m) _Pragma("unroll") for (int k = 0; k < 2; ++k) dst[m][k] = *(const PG8_LAS bf16x8*)(lds + PG8_SA(b, h) + aoff + m * 2048 + k * 1024); } while (0)
; #define PG8_MMA(ai, bj, At, Bt) do { __builtin_amdgcn_s_setprio(1); _Pragma("unroll") for (int m = 0; m < 4; ++m) _Pragma("unroll") for (int n = 0; n < 2; ++n) _Pragma("unroll") for (int k = 0; k < 2; ++k) \
;         acc[ai][bj][m][n] = __builtin_amdgcn_mfma_f32_16x16x32_bf16(Bt[n][k], At[m][k], acc[ai][bj][m][n], 0, 0, 0); __builtin_amdgcn_s_setprio(0); } while (0)
; #define PG8_WAIT_V(n) asm volatile("s_waitcnt vmcnt(" #n ")" ::: "memory")
; #define PG8_WAIT_L(n) asm volatile("s_waitcnt lgkmcnt(" #n ")" ::: "memory")
; #define PG8_BAR __builtin_amdgcn_s_barrier()
; #define PG8_SCHED __builtin_amdgcn_sched_barrier(0)
; template <class Epi, class Sched, bool ALIGN_EPI = false, bool SP2 = false>
; __device__ __forceinline__ void gemm_phase(PG8_LAS unsigned char* lds, const Gemm g, const Sched& S, const Epi& E) {
;     ...
;             PG8_WAIT_V(8); PG8_WAIT_L(0); PG8_BAR; PG8_MMA(0, 0, At, B0); PG8_MMA(0, 1, At, B1); PG8_BAR; PG8_SCHED;
;             PG8_LDA(At, 1, 1); PG8_STAGE(PG8_SB(1, 0), b3, voffB); PG8_STAGE(PG8_SB(1, 1), b3 + hstep, voffB); PG8_STAGE(PG8_SA(1, 0), a3, voffA);
;             PG8_WAIT_V(8); PG8_WAIT_L(0); PG8_BAR; PG8_MMA(1, 0, At, B0); PG8_MMA(1, 1, At, B1); PG8_BAR; PG8_SCHED;
	s_add_i32 s2, s2, s58
	v_lshl_add_u64 v[8:9], v[220:221], 0, s[22:23]
	s_mov_b32 m0, s2
	ds_read_b128 v[166:169], v210 offset:49152
	ds_read_b128 v[170:173], v210 offset:50176
	ds_read_b128 v[174:177], v210 offset:51200
	ds_read_b128 v[178:181], v210 offset:52224
	ds_read_b128 v[182:185], v210 offset:53248
	ds_read_b128 v[186:189], v210 offset:54272
	ds_read_b128 v[212:215], v210 offset:55296
	ds_read_b128 v[216:219], v210 offset:56320
	global_load_lds_dwordx4 v[8:9], off
	s_add_i32 m0, s2, 0x2000
	s_add_u32 s62, s62, 0x40080
	v_lshl_add_u64 v[8:9], v[222:223], 0, s[22:23]
	s_addc_u32 s63, s63, 0
	s_add_i32 s2, s95, s58
	global_load_lds_dwordx4 v[8:9], off
	v_lshl_add_u64 v[8:9], s[62:63], 0, v[192:193]
	s_mov_b32 m0, s2
	s_nop 0
	global_load_lds_dwordx4 v[8:9], off
	v_lshl_add_u64 v[8:9], s[62:63], 0, v[196:197]
	s_add_i32 m0, s2, 0x2000
	s_nop 0
	global_load_lds_dwordx4 v[8:9], off
	v_lshl_add_u64 v[8:9], v[224:225], 0, s[22:23]
	s_mov_b32 m0, s72
	s_nop 0
	global_load_lds_dwordx4 v[8:9], off
	v_lshl_add_u64 v[8:9], v[226:227], 0, s[22:23]
	s_mov_b32 m0, s73
	s_nop 0
	global_load_lds_dwordx4 v[8:9], off
	s_waitcnt vmcnt(8)
	s_waitcnt lgkmcnt(0)
	s_barrier
	s_waitcnt lgkmcnt(0)
	v_mfma_f32_16x16x32_bf16 v[66:69], v[134:137], v[166:169], v[66:69]
	v_mfma_f32_16x16x32_bf16 v[62:65], v[142:145], v[166:169], v[62:65]
	v_mfma_f32_16x16x32_bf16 v[50:53], v[134:137], v[174:177], v[50:53]
	v_mfma_f32_16x16x32_bf16 v[46:49], v[142:145], v[174:177], v[46:49]
	v_mfma_f32_16x16x32_bf16 v[34:37], v[134:137], v[182:185], v[34:37]
	v_mfma_f32_16x16x32_bf16 v[30:33], v[142:145], v[182:185], v[30:33]
	v_mfma_f32_16x16x32_bf16 v[18:21], v[134:137], v[212:215], v[18:21]
	v_mfma_f32_16x16x32_bf16 v[14:17], v[142:145], v[212:215], v[14:17]
	v_mfma_f32_16x16x32_bf16 v[66:69], v[138:141], v[170:173], v[66:69]
	v_mfma_f32_16x16x32_bf16 v[62:65], v[146:149], v[170:173], v[62:65]
	v_mfma_f32_16x16x32_bf16 v[50:53], v[138:141], v[178:181], v[50:53]
	v_mfma_f32_16x16x32_bf16 v[46:49], v[146:149], v[178:181], v[46:49]
	v_mfma_f32_16x16x32_bf16 v[34:37], v[138:141], v[186:189], v[34:37]
	v_mfma_f32_16x16x32_bf16 v[30:33], v[146:149], v[186:189], v[30:33]
	v_mfma_f32_16x16x32_bf16 v[18:21], v[138:141], v[216:219], v[18:21]
	v_mfma_f32_16x16x32_bf16 v[14:17], v[146:149], v[216:219], v[14:17]
	v_mfma_f32_16x16x32_bf16 v[58:61], v[150:153], v[166:169], v[58:61]
	v_mfma_f32_16x16x32_bf16 v[54:57], v[158:161], v[166:169], v[54:57]
	v_mfma_f32_16x16x32_bf16 v[42:45], v[150:153], v[174:177], v[42:45]
	v_mfma_f32_16x16x32_bf16 v[38:41], v[158:161], v[174:177], v[38:41]
	v_mfma_f32_16x16x32_bf16 v[26:29], v[150:153], v[182:185], v[26:29]
	v_mfma_f32_16x16x32_bf16 v[22:25], v[158:161], v[182:185], v[22:25]
	v_mfma_f32_16x16x32_bf16 v[8:11], v[150:153], v[212:215], v[10:13]
	v_mfma_f32_16x16x32_bf16 v[4:7], v[158:161], v[212:215], v[4:7]
	v_mfma_f32_16x16x32_bf16 v[58:61], v[154:157], v[170:173], v[58:61]
	v_mfma_f32_16x16x32_bf16 v[54:57], v[162:165], v[170:173], v[54:57]
	v_mfma_f32_16x16x32_bf16 v[42:45], v[154:157], v[178:181], v[42:45]
	v_mfma_f32_16x16x32_bf16 v[38:41], v[162:165], v[178:181], v[38:41]
	v_mfma_f32_16x16x32_bf16 v[26:29], v[154:157], v[186:189], v[26:29]
	v_mfma_f32_16x16x32_bf16 v[22:25], v[162:165], v[186:189], v[22:25]
	v_mfma_f32_16x16x32_bf16 v[10:13], v[154:157], v[216:219], v[8:11]
	v_mfma_f32_16x16x32_bf16 v[6:9], v[162:165], v[216:219], v[4:7]
	s_barrier
	s_add_i32 s94, s94, 2
	s_add_u32 s60, s60, 0x100
	s_addc_u32 s61, s61, 0
	s_cmp_gt_u32 s94, 13
	s_cbranch_scc1 .LBB0_590

; #define PG8_STAGE(bufoff, gbase, voff) do { _Pragma("unroll") for (int _i = 0; _i < 2; ++_i) \
;         __builtin_amdgcn_global_load_lds((const unsigned*)((const char*)(gbase) + (voff)[_i]), (PG8_LAS unsigned*)(lds + (bufoff) + ldsw + _i * 8192), 16, 0, 0); } while (0)
; #define PG8_LDA(dst, b, h) do { _Pragma("unroll") for (int m = 0; m < 4; ++m) _Pragma("unroll") for (int k = 0; k < 2; ++k) dst[m][k] = *(const PG8_LAS bf16x8*)(lds + PG8_SA(b, h) + aoff + m * 2048 + k * 1024); } while (0)
; #define PG8_LDB(dst, b, h) do { _Pragma("unroll") for (int n = 0; n < 2; ++n) _Pragma("unroll") for (int k = 0; k < 2; ++k) dst[n][k] = *(const PG8_LAS bf16x8*)(lds + PG8_SB(b, h) + boff + n * 2048 + k * 1024); } while (0)
; #define PG8_MMA(ai, bj, At, Bt) do { __builtin_amdgcn_s_setprio(1); _Pragma("unroll") for (int m = 0; m < 4; ++m) _Pragma("unroll") for (int n = 0; n < 2; ++n) _Pragma("unroll") for (int k = 0; k < 2; ++k) \
;         acc[ai][bj][m][n] = __builtin_amdgcn_mfma_f32_16x16x32_bf16(Bt[n][k], At[m][k], acc[ai][bj][m][n], 0, 0, 0); __builtin_amdgcn_s_setprio(0); } while (0)
; #define PG8_WAIT_V(n) asm volatile("s_waitcnt vmcnt(" #n ")" ::: "memory")
; #define PG8_WAIT_L(n) asm volatile("s_waitcnt lgkmcnt(" #n ")" ::: "memory")
; #define PG8_BAR __builtin_amdgcn_s_barrier()
; #define PG8_SCHED __builtin_amdgcn_sched_barrier(0)
; template <class Epi, class Sched, bool ALIGN_EPI = false, bool SP2 = false>
; __device__ __forceinline__ void gemm_phase(PG8_LAS unsigned char* lds, const Gemm g, const Sched& S, const Epi& E) {
;     ...
;             PG8_LDB(B0, 0, 0); PG8_LDB(B1, 0, 1); PG8_SCHED; PG8_LDA(At, 0, 0); PG8_STAGE(PG8_SA(1, 1), a1 + hstep, voffA);
;             PG8_WAIT_V(8); PG8_WAIT_L(0); PG8_BAR; PG8_MMA(0, 0, At, B0); PG8_MMA(0, 1, At, B1); PG8_BAR; PG8_SCHED;
;             PG8_LDA(At, 0, 1); PG8_STAGE(PG8_SB(0, 0), b2, voffB); PG8_STAGE(PG8_SB(0, 1), b2 + hstep, voffB); PG8_STAGE(PG8_SA(0, 0), a2, voffA);
;             PG8_WAIT_V(8); PG8_WAIT_L(0); PG8_BAR; PG8_MMA(1, 0, At, B0); PG8_MMA(1, 1, At, B1); PG8_BAR; PG8_SCHED;
.LBB0_722:
	v_add_u32_e32 v140, s74, v138
	ds_read_b128 v[144:147], v140
	ds_read_b128 v[148:151], v140 offset:1024
	ds_read_b128 v[152:155], v140 offset:2048
	ds_read_b128 v[156:159], v140 offset:3072
	v_add_u32_e32 v140, s75, v138
	ds_read_b128 v[160:163], v140
	ds_read_b128 v[164:167], v140 offset:1024
	ds_read_b128 v[168:171], v140 offset:2048
	ds_read_b128 v[172:175], v140 offset:3072
	s_add_u32 s2, s48, 0xfffc0080
	s_addc_u32 s46, s49, -1
	s_cmp_eq_u32 s80, 12
	s_cselect_b32 s53, s29, s46
	s_cselect_b32 s52, s31, s2
	s_cselect_b32 s47, s39, s79
	s_cselect_b32 s46, s77, s78
	v_lshl_add_u64 v[140:141], s[48:49], 0, v[0:1]
	s_add_i32 m0, s64, 0xc000
	ds_read_b128 v[176:179], v139
	ds_read_b128 v[180:183], v139 offset:1024
	ds_read_b128 v[184:187], v139 offset:2048
	ds_read_b128 v[188:191], v139 offset:3072
	ds_read_b128 v[192:195], v139 offset:4096
	ds_read_b128 v[196:199], v139 offset:5120
	ds_read_b128 v[200:203], v139 offset:6144
	ds_read_b128 v[204:207], v139 offset:7168
	global_load_lds_dwordx4 v[140:141], off
	v_lshl_add_u64 v[140:141], s[48:49], 0, v[134:135]
	s_add_i32 m0, s64, 0xe000
	s_nop 0
	global_load_lds_dwordx4 v[140:141], off
	s_waitcnt vmcnt(12)
	s_waitcnt lgkmcnt(0)
	s_barrier
	s_waitcnt lgkmcnt(0)
	v_mfma_f32_16x16x32_bf16 v[2:5], v[144:147], v[176:179], v[2:5]
	v_mfma_f32_16x16x32_bf16 v[6:9], v[152:155], v[176:179], v[6:9]
	v_mfma_f32_16x16x32_bf16 v[22:25], v[144:147], v[184:187], v[22:25]
	v_mfma_f32_16x16x32_bf16 v[18:21], v[152:155], v[184:187], v[18:21]
	v_mfma_f32_16x16x32_bf16 v[38:41], v[144:147], v[192:195], v[38:41]
	v_mfma_f32_16x16x32_bf16 v[34:37], v[152:155], v[192:195], v[34:37]
	v_mfma_f32_16x16x32_bf16 v[54:57], v[144:147], v[200:203], v[54:57]
	v_mfma_f32_16x16x32_bf16 v[50:53], v[152:155], v[200:203], v[50:53]
	v_mfma_f32_16x16x32_bf16 v[2:5], v[148:151], v[180:183], v[2:5]
	v_mfma_f32_16x16x32_bf16 v[6:9], v[156:159], v[180:183], v[6:9]
	v_mfma_f32_16x16x32_bf16 v[22:25], v[148:151], v[188:191], v[22:25]
	v_mfma_f32_16x16x32_bf16 v[18:21], v[156:159], v[188:191], v[18:21]
	v_mfma_f32_16x16x32_bf16 v[38:41], v[148:151], v[196:199], v[38:41]
	v_mfma_f32_16x16x32_bf16 v[34:37], v[156:159], v[196:199], v[34:37]
	v_mfma_f32_16x16x32_bf16 v[54:57], v[148:151], v[204:207], v[54:57]
	v_mfma_f32_16x16x32_bf16 v[50:53], v[156:159], v[204:207], v[50:53]
	v_mfma_f32_16x16x32_bf16 v[10:13], v[160:163], v[176:179], v[10:13]
	v_mfma_f32_16x16x32_bf16 v[14:17], v[168:171], v[176:179], v[14:17]
	v_mfma_f32_16x16x32_bf16 v[26:29], v[160:163], v[184:187], v[26:29]
	v_mfma_f32_16x16x32_bf16 v[30:33], v[168:171], v[184:187], v[30:33]
	v_mfma_f32_16x16x32_bf16 v[42:45], v[160:163], v[192:195], v[42:45]
	v_mfma_f32_16x16x32_bf16 v[46:49], v[168:171], v[192:195], v[46:49]
	v_mfma_f32_16x16x32_bf16 v[58:61], v[160:163], v[200:203], v[58:61]
	v_mfma_f32_16x16x32_bf16 v[62:65], v[168:171], v[200:203], v[62:65]
	v_mfma_f32_16x16x32_bf16 v[10:13], v[164:167], v[180:183], v[10:13]
	v_mfma_f32_16x16x32_bf16 v[14:17], v[172:175], v[180:183], v[14:17]
	v_mfma_f32_16x16x32_bf16 v[26:29], v[164:167], v[188:191], v[26:29]
	v_mfma_f32_16x16x32_bf16 v[30:33], v[172:175], v[188:191], v[30:33]
	v_mfma_f32_16x16x32_bf16 v[42:45], v[164:167], v[196:199], v[42:45]
	v_mfma_f32_16x16x32_bf16 v[46:49], v[172:175], v[196:199], v[46:49]
	v_mfma_f32_16x16x32_bf16 v[58:61], v[164:167], v[204:207], v[58:61]
	v_mfma_f32_16x16x32_bf16 v[62:65], v[172:175], v[204:207], v[62:65]
	s_barrier
	s_add_i32 s2, s74, s57
	v_lshl_add_u64 v[140:141], s[46:47], 0, v[130:131]
	s_mov_b32 m0, s2
	ds_read_b128 v[176:179], v139 offset:16384
	ds_read_b128 v[180:183], v139 offset:17408
	ds_read_b128 v[184:187], v139 offset:18432
	ds_read_b128 v[188:191], v139 offset:19456
	ds_read_b128 v[192:195], v139 offset:20480
	ds_read_b128 v[196:199], v139 offset:21504
	ds_read_b128 v[200:203], v139 offset:22528
	ds_read_b128 v[204:207], v139 offset:23552
	global_load_lds_dwordx4 v[140:141], off
	s_add_i32 m0, s2, 0x2000
	s_add_u32 s82, s46, 0x40000
	v_lshl_add_u64 v[208:209], s[46:47], 0, v[132:133]
	s_addc_u32 s83, s47, 0
	s_add_i32 s2, s75, s57
	global_load_lds_dwordx4 v[208:209], off
	v_lshl_add_u64 v[210:211], s[82:83], 0, v[130:131]
	s_mov_b32 m0, s2
	v_lshl_add_u64 v[212:213], s[52:53], 0, v[132:133]
	global_load_lds_dwordx4 v[210:211], off
	v_lshl_add_u64 v[210:211], s[82:83], 0, v[132:133]
	s_add_i32 m0, s2, 0x2000
	s_nop 0
	global_load_lds_dwordx4 v[210:211], off
	v_lshl_add_u64 v[210:211], s[52:53], 0, v[130:131]
	s_mov_b32 m0, s64
	s_nop 0
	global_load_lds_dwordx4 v[210:211], off
	s_mov_b32 m0, s65
	s_nop 0
	global_load_lds_dwordx4 v[212:213], off
	s_waitcnt vmcnt(12)
	s_waitcnt lgkmcnt(0)
	s_barrier
; #define PG8_STAGE(bufoff, gbase, voff) do { _Pragma("unroll") for (int _i = 0; _i < 2; ++_i) \
;         __builtin_amdgcn_global_load_lds((const unsigned*)((const char*)(gbase) + (voff)[_i]), (PG8_LAS unsigned*)(lds + (bufoff) + ldsw + _i * 8192), 16, 0, 0); } while (0)
; #define PG8_LDA(dst, b, h) do { _Pragma("unroll") for (int m = 0; m < 4; ++m) _Pragma("unroll") for (int k = 0; k < 2; ++k) dst[m][k] = *(const PG8_LAS bf16x8*)(lds + PG8_SA(b, h) + aoff + m * 2048 + k * 1024); } while (0)
; #define PG8_LDB(dst, b, h) do { _Pragma("unroll") for (int n = 0; n < 2; ++n) _Pragma("unroll") for (int k = 0; k < 2; ++k) dst[n][k] = *(const PG8_LAS bf16x8*)(lds + PG8_SB(b, h) + boff + n * 2048 + k * 1024); } while (0)
; #define PG8_MMA(ai, bj, At, Bt) do { __builtin_amdgcn_s_setprio(1); _Pragma("unroll") for (int m = 0; m < 4; ++m) _Pragma("unroll") for (int n = 0; n < 2; ++n) _Pragma("unroll") for (int k = 0; k < 2; ++k) \
;         acc[ai][bj][m][n] = __builtin_amdgcn_mfma_f32_16x16x32_bf16(Bt[n][k], At[m][k], acc[ai][bj][m][n], 0, 0, 0); __builtin_amdgcn_s_setprio(0); } while (0)
; #define PG8_WAIT_V(n) asm volatile("s_waitcnt vmcnt(" #n ")" ::: "memory")
; #define PG8_WAIT_L(n) asm volatile("s_waitcnt lgkmcnt(" #n ")" ::: "memory")
; #define PG8_BAR __builtin_amdgcn_s_barrier()
; #define PG8_SCHED __builtin_amdgcn_sched_barrier(0)
; template <class Epi, class Sched, bool ALIGN_EPI = false, bool SP2 = false>
; __device__ __forceinline__ void gemm_phase(PG8_LAS unsigned char* lds, const Gemm g, const Sched& S, const Epi& E) {
;     ...
;             PG8_LDA(At, 0, 1); PG8_STAGE(PG8_SB(0, 0), b2, voffB); PG8_STAGE(PG8_SB(0, 1), b2 + hstep, voffB); PG8_STAGE(PG8_SA(0, 0), a2, voffA);
;             PG8_WAIT_V(8); PG8_WAIT_L(0); PG8_BAR; PG8_MMA(1, 0, At, B0); PG8_MMA(1, 1, At, B1); PG8_BAR; PG8_SCHED;
;             PG8_LDB(B0, 1, 0); PG8_LDB(B1, 1, 1); PG8_SCHED; PG8_LDA(At, 1, 0); PG8_STAGE(PG8_SA(0, 1), a2 + hstep, voffA);
;             PG8_WAIT_V(8); PG8_WAIT_L(0); PG8_BAR; PG8_MMA(0, 0, At, B0); PG8_MMA(0, 1, At, B1); PG8_BAR; PG8_SCHED;
	s_waitcnt lgkmcnt(0)
	v_mfma_f32_16x16x32_bf16 v[70:73], v[144:147], v[176:179], v[70:73]
	v_mfma_f32_16x16x32_bf16 v[66:69], v[152:155], v[176:179], v[66:69]
	v_mfma_f32_16x16x32_bf16 v[86:89], v[144:147], v[184:187], v[86:89]
	v_mfma_f32_16x16x32_bf16 v[82:85], v[152:155], v[184:187], v[82:85]
	v_mfma_f32_16x16x32_bf16 v[102:105], v[144:147], v[192:195], v[102:105]
	v_mfma_f32_16x16x32_bf16 v[98:101], v[152:155], v[192:195], v[98:101]
	v_mfma_f32_16x16x32_bf16 v[118:121], v[144:147], v[200:203], v[118:121]
	v_mfma_f32_16x16x32_bf16 v[114:117], v[152:155], v[200:203], v[114:117]
	v_mfma_f32_16x16x32_bf16 v[70:73], v[148:151], v[180:183], v[70:73]
	v_mfma_f32_16x16x32_bf16 v[66:69], v[156:159], v[180:183], v[66:69]
	v_mfma_f32_16x16x32_bf16 v[86:89], v[148:151], v[188:191], v[86:89]
	v_mfma_f32_16x16x32_bf16 v[82:85], v[156:159], v[188:191], v[82:85]
	v_mfma_f32_16x16x32_bf16 v[102:105], v[148:151], v[196:199], v[102:105]
	v_mfma_f32_16x16x32_bf16 v[98:101], v[156:159], v[196:199], v[98:101]
	v_mfma_f32_16x16x32_bf16 v[118:121], v[148:151], v[204:207], v[118:121]
	v_mfma_f32_16x16x32_bf16 v[114:117], v[156:159], v[204:207], v[114:117]
	v_mfma_f32_16x16x32_bf16 v[74:77], v[160:163], v[176:179], v[74:77]
	v_mfma_f32_16x16x32_bf16 v[78:81], v[168:171], v[176:179], v[78:81]
	v_mfma_f32_16x16x32_bf16 v[90:93], v[160:163], v[184:187], v[90:93]
	v_mfma_f32_16x16x32_bf16 v[94:97], v[168:171], v[184:187], v[94:97]
	v_mfma_f32_16x16x32_bf16 v[106:109], v[160:163], v[192:195], v[106:109]
	v_mfma_f32_16x16x32_bf16 v[110:113], v[168:171], v[192:195], v[110:113]
	v_mfma_f32_16x16x32_bf16 v[122:125], v[160:163], v[200:203], v[122:125]
	v_mfma_f32_16x16x32_bf16 v[126:129], v[168:171], v[200:203], v[126:129]
	v_mfma_f32_16x16x32_bf16 v[74:77], v[164:167], v[180:183], v[74:77]
	v_mfma_f32_16x16x32_bf16 v[78:81], v[172:175], v[180:183], v[78:81]
	v_mfma_f32_16x16x32_bf16 v[90:93], v[164:167], v[188:191], v[90:93]
	v_mfma_f32_16x16x32_bf16 v[94:97], v[172:175], v[188:191], v[94:97]
	v_mfma_f32_16x16x32_bf16 v[106:109], v[164:167], v[196:199], v[106:109]
	v_mfma_f32_16x16x32_bf16 v[110:113], v[172:175], v[196:199], v[110:113]
	v_mfma_f32_16x16x32_bf16 v[122:125], v[164:167], v[204:207], v[122:125]
	v_mfma_f32_16x16x32_bf16 v[126:129], v[172:175], v[204:207], v[126:129]
	s_barrier
	s_add_i32 s2, 0, 0x18000
	s_add_i32 s81, 0, 0x1c000
	v_add_u32_e32 v156, s2, v138
	v_add_u32_e32 v172, s81, v138
	ds_read_b128 v[144:147], v156
	ds_read_b128 v[148:151], v156 offset:1024
	ds_read_b128 v[152:155], v156 offset:2048
	ds_read_b128 v[156:159], v156 offset:3072
	ds_read_b128 v[160:163], v172
	ds_read_b128 v[164:167], v172 offset:1024
	ds_read_b128 v[168:171], v172 offset:2048
	ds_read_b128 v[172:175], v172 offset:3072
	s_add_u32 s52, s52, 0x40000
	s_addc_u32 s53, s53, 0
	s_mov_b32 m0, s66
	v_lshl_add_u64 v[214:215], s[52:53], 0, v[130:131]
	ds_read_b128 v[176:179], v139 offset:32768
	ds_read_b128 v[180:183], v139 offset:33792
	ds_read_b128 v[184:187], v139 offset:34816
	ds_read_b128 v[188:191], v139 offset:35840
	ds_read_b128 v[192:195], v139 offset:36864
	ds_read_b128 v[196:199], v139 offset:37888
	ds_read_b128 v[200:203], v139 offset:38912
	ds_read_b128 v[204:207], v139 offset:39936
	global_load_lds_dwordx4 v[214:215], off
	v_lshl_add_u64 v[214:215], s[52:53], 0, v[132:133]
	s_mov_b32 m0, s67
	s_nop 0
	global_load_lds_dwordx4 v[214:215], off
	s_waitcnt vmcnt(8)
	s_waitcnt lgkmcnt(0)
	s_barrier
; #define PG8_STAGE(bufoff, gbase, voff) do { _Pragma("unroll") for (int _i = 0; _i < 2; ++_i) \
;         __builtin_amdgcn_global_load_lds((const unsigned*)((const char*)(gbase) + (voff)[_i]), (PG8_LAS unsigned*)(lds + (bufoff) + ldsw + _i * 8192), 16, 0, 0); } while (0)
; #define PG8_LDA(dst, b, h) do { _Pragma("unroll") for (int m = 0; m < 4; ++m) _Pragma("unroll") for (int k = 0; k < 2; ++k) dst[m][k] = *(const PG8_LAS bf16x8*)(lds + PG8_SA(b, h) + aoff + m * 2048 + k * 1024); } while (0)
; #define PG8_MMA(ai, bj, At, Bt) do { __builtin_amdgcn_s_setprio(1); _Pragma("unroll") for (int m = 0; m < 4; ++m) _Pragma("unroll") for (int n = 0; n < 2; ++n) _Pragma("unroll") for (int k = 0; k < 2; ++k) \
;         acc[ai][bj][m][n] = __builtin_amdgcn_mfma_f32_16x16x32_bf16(Bt[n][k], At[m][k], acc[ai][bj][m][n], 0, 0, 0); __builtin_amdgcn_s_setprio(0); } while (0)
; #define PG8_WAIT_V(n) asm volatile("s_waitcnt vmcnt(" #n ")" ::: "memory")
; #define PG8_WAIT_L(n) asm volatile("s_waitcnt lgkmcnt(" #n ")" ::: "memory")
; #define PG8_BAR __builtin_amdgcn_s_barrier()
; #define PG8_SCHED __builtin_amdgcn_sched_barrier(0)
;     __device__ __forceinline__ void init(f32x4 (&acc)[2][2][4][2], const Unit& u, int wr, int wc, int fr, int fq) const {
;     ...
;             for (int m = 0; m < 4; ++m) { const size_t off = ((size_t)u.pm * 256 + 128 * ai + 64 * wr + 16 * m + fr) * DM + u.pn * 256 + 32 * wc + 4 * fq;
; #pragma unroll
;                 for (int bj = 0; bj < 2; ++bj)
; #pragma unroll
;                     for (int n = 0; n < 2; ++n) acc[ai][bj][m][n] = __builtin_nontemporal_load((const f32x4*)(x + off + bj * HALF + n * 16)); }
; template <class Epi, class Sched, bool ALIGN_EPI = false, bool SP2 = false>
; __device__ __forceinline__ void gemm_phase(PG8_LAS unsigned char* lds, const Gemm g, const Sched& S, const Epi& E) {
;     ...
;             PG8_WAIT_V(8); PG8_WAIT_L(0); PG8_BAR; PG8_MMA(0, 0, At, B0); PG8_MMA(0, 1, At, B1); PG8_BAR; PG8_SCHED;
;             PG8_LDA(At, 1, 1); PG8_STAGE(PG8_SB(1, 0), b3, voffB); PG8_STAGE(PG8_SB(1, 1), b3 + hstep, voffB); PG8_STAGE(PG8_SA(1, 0), a3, voffA);
;             PG8_WAIT_V(8); PG8_WAIT_L(0); PG8_BAR; PG8_MMA(1, 0, At, B0); PG8_MMA(1, 1, At, B1); PG8_BAR; PG8_SCHED;
	s_waitcnt lgkmcnt(0)
	v_mfma_f32_16x16x32_bf16 v[2:5], v[144:147], v[176:179], v[2:5]
	v_mfma_f32_16x16x32_bf16 v[6:9], v[152:155], v[176:179], v[6:9]
	v_mfma_f32_16x16x32_bf16 v[22:25], v[144:147], v[184:187], v[22:25]
	v_mfma_f32_16x16x32_bf16 v[18:21], v[152:155], v[184:187], v[18:21]
	v_mfma_f32_16x16x32_bf16 v[38:41], v[144:147], v[192:195], v[38:41]
	v_mfma_f32_16x16x32_bf16 v[34:37], v[152:155], v[192:195], v[34:37]
	v_mfma_f32_16x16x32_bf16 v[54:57], v[144:147], v[200:203], v[54:57]
	v_mfma_f32_16x16x32_bf16 v[50:53], v[152:155], v[200:203], v[50:53]
	v_mfma_f32_16x16x32_bf16 v[2:5], v[148:151], v[180:183], v[2:5]
	v_mfma_f32_16x16x32_bf16 v[6:9], v[156:159], v[180:183], v[6:9]
	v_mfma_f32_16x16x32_bf16 v[22:25], v[148:151], v[188:191], v[22:25]
	v_mfma_f32_16x16x32_bf16 v[18:21], v[156:159], v[188:191], v[18:21]
	v_mfma_f32_16x16x32_bf16 v[38:41], v[148:151], v[196:199], v[38:41]
	v_mfma_f32_16x16x32_bf16 v[34:37], v[156:159], v[196:199], v[34:37]
	v_mfma_f32_16x16x32_bf16 v[54:57], v[148:151], v[204:207], v[54:57]
	v_mfma_f32_16x16x32_bf16 v[50:53], v[156:159], v[204:207], v[50:53]
	v_mfma_f32_16x16x32_bf16 v[10:13], v[160:163], v[176:179], v[10:13]
	v_mfma_f32_16x16x32_bf16 v[14:17], v[168:171], v[176:179], v[14:17]
	v_mfma_f32_16x16x32_bf16 v[26:29], v[160:163], v[184:187], v[26:29]
	v_mfma_f32_16x16x32_bf16 v[30:33], v[168:171], v[184:187], v[30:33]
	v_mfma_f32_16x16x32_bf16 v[42:45], v[160:163], v[192:195], v[42:45]
	v_mfma_f32_16x16x32_bf16 v[46:49], v[168:171], v[192:195], v[46:49]
	v_mfma_f32_16x16x32_bf16 v[58:61], v[160:163], v[200:203], v[58:61]
	v_mfma_f32_16x16x32_bf16 v[62:65], v[168:171], v[200:203], v[62:65]
	v_mfma_f32_16x16x32_bf16 v[10:13], v[164:167], v[180:183], v[10:13]
	v_mfma_f32_16x16x32_bf16 v[14:17], v[172:175], v[180:183], v[14:17]
	v_mfma_f32_16x16x32_bf16 v[26:29], v[164:167], v[188:191], v[26:29]
	v_mfma_f32_16x16x32_bf16 v[30:33], v[172:175], v[188:191], v[30:33]
	v_mfma_f32_16x16x32_bf16 v[42:45], v[164:167], v[196:199], v[42:45]
	v_mfma_f32_16x16x32_bf16 v[46:49], v[172:175], v[196:199], v[46:49]
	v_mfma_f32_16x16x32_bf16 v[58:61], v[164:167], v[204:207], v[58:61]
	v_mfma_f32_16x16x32_bf16 v[62:65], v[172:175], v[204:207], v[62:65]
	s_barrier
	s_add_i32 s2, s2, s57
	v_lshl_add_u64 v[140:141], v[140:141], 0, s[26:27]
	s_mov_b32 m0, s2
	ds_read_b128 v[176:179], v139 offset:49152
	ds_read_b128 v[180:183], v139 offset:50176
	ds_read_b128 v[184:187], v139 offset:51200
	ds_read_b128 v[188:191], v139 offset:52224
	ds_read_b128 v[192:195], v139 offset:53248
	ds_read_b128 v[196:199], v139 offset:54272
	ds_read_b128 v[200:203], v139 offset:55296
	ds_read_b128 v[204:207], v139 offset:56320
	global_load_lds_dwordx4 v[140:141], off
	s_add_i32 m0, s2, 0x2000
	s_add_u32 s46, s46, 0x40080
	v_lshl_add_u64 v[140:141], v[208:209], 0, s[26:27]
	s_addc_u32 s47, s47, 0
	s_add_i32 s2, s81, s57
	global_load_lds_dwordx4 v[140:141], off
	v_lshl_add_u64 v[140:141], s[46:47], 0, v[130:131]
	s_mov_b32 m0, s2
	s_nop 0
	global_load_lds_dwordx4 v[140:141], off
	v_lshl_add_u64 v[140:141], s[46:47], 0, v[132:133]
	s_add_i32 m0, s2, 0x2000
	s_nop 0
	global_load_lds_dwordx4 v[140:141], off
	v_lshl_add_u64 v[140:141], v[210:211], 0, s[26:27]
	s_mov_b32 m0, s68
	s_nop 0
	global_load_lds_dwordx4 v[140:141], off
	v_lshl_add_u64 v[140:141], v[212:213], 0, s[26:27]
	s_mov_b32 m0, s69
	s_nop 0
	global_load_lds_dwordx4 v[140:141], off
	s_cmp_lt_i32 s80, 6
	s_cbranch_scc0 .Lxa_hi
	s_cmp_lt_i32 s80, 2
	s_cbranch_scc0 .Lxa_23
	s_cmp_lt_i32 s80, 0
	s_cbranch_scc0 .Lxa_1
	v_add_f32_e32 v2, v2, v216
	v_add_f32_e32 v3, v3, v217
	v_add_f32_e32 v4, v4, v218
	v_add_f32_e32 v5, v5, v219
	v_add_f32_e32 v6, v6, v220
	v_add_f32_e32 v7, v7, v221
	v_add_f32_e32 v8, v8, v222
	v_add_f32_e32 v9, v9, v223
	v_add_f32_e32 v10, v10, v224
	v_add_f32_e32 v11, v11, v225
	v_add_f32_e32 v12, v12, v226
	v_add_f32_e32 v13, v13, v227
	v_add_f32_e32 v14, v14, v228
	v_add_f32_e32 v15, v15, v229
	v_add_f32_e32 v16, v16, v230
	v_add_f32_e32 v17, v17, v231
	s_branch .Lxa_done

; #define PG8_MMA(ai, bj, At, Bt) do { __builtin_amdgcn_s_setprio(1); _Pragma("unroll") for (int m = 0; m < 4; ++m) _Pragma("unroll") for (int n = 0; n < 2; ++n) _Pragma("unroll") for (int k = 0; k < 2; ++k) \
;         acc[ai][bj][m][n] = __builtin_amdgcn_mfma_f32_16x16x32_bf16(Bt[n][k], At[m][k], acc[ai][bj][m][n], 0, 0, 0); __builtin_amdgcn_s_setprio(0); } while (0)
; #define PG8_WAIT_V(n) asm volatile("s_waitcnt vmcnt(" #n ")" ::: "memory")
; #define PG8_WAIT_L(n) asm volatile("s_waitcnt lgkmcnt(" #n ")" ::: "memory")
; #define PG8_BAR __builtin_amdgcn_s_barrier()
; #define PG8_SCHED __builtin_amdgcn_sched_barrier(0)
;     __device__ __forceinline__ void init(f32x4 (&acc)[2][2][4][2], const Unit& u, int wr, int wc, int fr, int fq) const {
;     ...
;             for (int m = 0; m < 4; ++m) { const size_t off = ((size_t)u.pm * 256 + 128 * ai + 64 * wr + 16 * m + fr) * DM + u.pn * 256 + 32 * wc + 4 * fq;
; #pragma unroll
;                 for (int bj = 0; bj < 2; ++bj)
; #pragma unroll
;                     for (int n = 0; n < 2; ++n) acc[ai][bj][m][n] = __builtin_nontemporal_load((const f32x4*)(x + off + bj * HALF + n * 16)); }
; template <class Epi, class Sched, bool ALIGN_EPI = false, bool SP2 = false>
; __device__ __forceinline__ void gemm_phase(PG8_LAS unsigned char* lds, const Gemm g, const Sched& S, const Epi& E) {
;     ...
;             PG8_WAIT_V(8); PG8_WAIT_L(0); PG8_BAR; PG8_MMA(1, 0, At, B0); PG8_MMA(1, 1, At, B1); PG8_BAR; PG8_SCHED;
.Lxa_done:
	s_add_i32 s92, s80, 4
	s_and_b32 s93, s92, 6
	s_lshl_b32 s93, s93, 15
	s_and_b32 s92, s92, 8
	s_lshl_b32 s92, s92, 16
	s_add_i32 s92, s92, s93
	s_cmp_eq_u32 s80, 12
	s_cselect_b32 s90, s86, s84
	s_cselect_b32 s91, s87, s85
	s_add_u32 s90, s90, s92
	s_addc_u32 s91, s91, 0
	v_lshl_add_u64 v[232:233], v[234:235], 0, s[90:91]
	global_load_dwordx4 v[216:219], v[232:233], off nt
	global_load_dwordx4 v[220:223], v[232:233], off offset:64 nt
	global_load_dwordx4 v[224:227], v[232:233], off offset:512 nt
	global_load_dwordx4 v[228:231], v[232:233], off offset:576 nt
	s_waitcnt vmcnt(12)
	s_waitcnt lgkmcnt(0)
	s_barrier
	s_waitcnt lgkmcnt(0)
	v_mfma_f32_16x16x32_bf16 v[70:73], v[144:147], v[176:179], v[70:73]
	v_mfma_f32_16x16x32_bf16 v[66:69], v[152:155], v[176:179], v[66:69]
	v_mfma_f32_16x16x32_bf16 v[86:89], v[144:147], v[184:187], v[86:89]
	v_mfma_f32_16x16x32_bf16 v[82:85], v[152:155], v[184:187], v[82:85]
	v_mfma_f32_16x16x32_bf16 v[102:105], v[144:147], v[192:195], v[102:105]
	v_mfma_f32_16x16x32_bf16 v[98:101], v[152:155], v[192:195], v[98:101]
	v_mfma_f32_16x16x32_bf16 v[118:121], v[144:147], v[200:203], v[118:121]
	v_mfma_f32_16x16x32_bf16 v[114:117], v[152:155], v[200:203], v[114:117]
	v_mfma_f32_16x16x32_bf16 v[70:73], v[148:151], v[180:183], v[70:73]
	v_mfma_f32_16x16x32_bf16 v[66:69], v[156:159], v[180:183], v[66:69]
	v_mfma_f32_16x16x32_bf16 v[86:89], v[148:151], v[188:191], v[86:89]
	v_mfma_f32_16x16x32_bf16 v[82:85], v[156:159], v[188:191], v[82:85]
	v_mfma_f32_16x16x32_bf16 v[102:105], v[148:151], v[196:199], v[102:105]
	v_mfma_f32_16x16x32_bf16 v[98:101], v[156:159], v[196:199], v[98:101]
	v_mfma_f32_16x16x32_bf16 v[118:121], v[148:151], v[204:207], v[118:121]
	v_mfma_f32_16x16x32_bf16 v[114:117], v[156:159], v[204:207], v[114:117]
	v_mfma_f32_16x16x32_bf16 v[74:77], v[160:163], v[176:179], v[74:77]
	v_mfma_f32_16x16x32_bf16 v[78:81], v[168:171], v[176:179], v[78:81]
	v_mfma_f32_16x16x32_bf16 v[90:93], v[160:163], v[184:187], v[90:93]
	v_mfma_f32_16x16x32_bf16 v[94:97], v[168:171], v[184:187], v[94:97]
	v_mfma_f32_16x16x32_bf16 v[106:109], v[160:163], v[192:195], v[106:109]
	v_mfma_f32_16x16x32_bf16 v[110:113], v[168:171], v[192:195], v[110:113]
	v_mfma_f32_16x16x32_bf16 v[122:125], v[160:163], v[200:203], v[122:125]
	v_mfma_f32_16x16x32_bf16 v[126:129], v[168:171], v[200:203], v[126:129]
	v_mfma_f32_16x16x32_bf16 v[74:77], v[164:167], v[180:183], v[74:77]
	v_mfma_f32_16x16x32_bf16 v[78:81], v[172:175], v[180:183], v[78:81]
	v_mfma_f32_16x16x32_bf16 v[90:93], v[164:167], v[188:191], v[90:93]
	v_mfma_f32_16x16x32_bf16 v[94:97], v[172:175], v[188:191], v[94:97]
	v_mfma_f32_16x16x32_bf16 v[106:109], v[164:167], v[196:199], v[106:109]
	v_mfma_f32_16x16x32_bf16 v[110:113], v[172:175], v[196:199], v[110:113]
	v_mfma_f32_16x16x32_bf16 v[122:125], v[164:167], v[204:207], v[122:125]
	v_mfma_f32_16x16x32_bf16 v[126:129], v[172:175], v[204:207], v[126:129]
	s_barrier
	s_add_i32 s80, s80, 2
	s_add_u32 s48, s48, 0x100
	s_addc_u32 s49, s49, 0
	s_add_u32 s78, s78, 0x100
	s_addc_u32 s79, s79, 0
	s_cmp_gt_u32 s80, 13
	s_cbranch_scc0 .LBB0_722
	s_and_b64 vcc, exec, s[34:35]
	s_cbranch_vccz .LBB0_725
	s_barrier
